# re-measure of v45 (k-blocked GEMM layout + LDS-staged HG scan + HG p4) for a same-sitting comparison
# speedup vs baseline: 1.0453x; 1.0453x over previous
.LBB0_872:
	s_or_b64 exec, exec, s[0:1]
	v_mad_u32_u24 v56, v67, s35, v60
	s_waitcnt lgkmcnt(0)
	s_barrier
	ds_read_b128 v[70:73], v56
	v_lshl_or_b32 v54, v53, 5, v67
	v_mad_u64_u32 v[54:55], s[0:1], v54, s35, v[60:61]
	ds_read_b128 v[60:63], v54 offset:35840
	ds_read_b128 v[74:77], v54 offset:35904
	ds_read_b128 v[78:81], v56 offset:64
	ds_read_b128 v[86:89], v56 offset:2304
	ds_read_b128 v[90:93], v56 offset:2368
	ds_read_b128 v[98:101], v56 offset:4608
	ds_read_b128 v[102:105], v56 offset:4672
	s_waitcnt lgkmcnt(6)
	v_mfma_f32_16x16x32_bf16 v[82:85], v[70:73], v[60:63], 0
	ds_read_b128 v[110:113], v56 offset:6912
	ds_read_b128 v[114:117], v56 offset:6976
	v_lshlrev_b32_e32 v55, 7, v67
	v_lshlrev_b64 v[26:27], 13, v[58:59]
	s_waitcnt lgkmcnt(5)
	v_mfma_f32_16x16x32_bf16 v[94:97], v[86:89], v[60:63], 0
	v_lshlrev_b64 v[58:59], 15, v[58:59]
	v_lshl_or_b32 v166, v53, 12, v55
	ds_read_b128 v[122:125], v56 offset:9216
	ds_read_b128 v[126:129], v56 offset:9280
	s_waitcnt lgkmcnt(5)
	v_mfma_f32_16x16x32_bf16 v[106:109], v[98:101], v[60:63], 0
	ds_read_b128 v[134:137], v56 offset:11520
	ds_read_b128 v[138:141], v56 offset:11584
	v_lshl_add_u64 v[58:59], s[8:9], 0, v[58:59]
	v_ashrrev_i32_e32 v167, 31, v166
	s_waitcnt lgkmcnt(5)
	v_mfma_f32_16x16x32_bf16 v[118:121], v[110:113], v[60:63], 0
	ds_read_b128 v[146:149], v56 offset:13824
	ds_read_b128 v[150:153], v56 offset:13888
	ds_read_b128 v[158:161], v56 offset:16128
	ds_read_b128 v[162:165], v56 offset:16192
	v_lshl_add_u64 v[166:167], v[166:167], 1, v[58:59]
	v_mfma_f32_16x16x32_bf16 v[82:85], v[78:81], v[74:77], v[82:85]
	v_lshlrev_b32_e32 v168, 1, v68
	v_mov_b32_e32 v169, v24
	v_lshl_add_u64 v[170:171], v[166:167], 0, v[168:169]
	v_mfma_f32_16x16x32_bf16 v[94:97], v[90:93], v[74:77], v[94:97]
	v_lshlrev_b32_e32 v52, 2, v52
	s_nop 2
	v_cvt_pk_bf16_f32 v58, v82, v83
	v_cvt_pk_bf16_f32 v59, v84, v85
	v_mfma_f32_16x16x32_bf16 v[106:109], v[102:105], v[74:77], v[106:109]
	global_store_dwordx2 v[170:171], v[58:59], off
	v_cvt_pk_bf16_f32 v58, v94, v95
	v_cvt_pk_bf16_f32 v59, v96, v97
	s_waitcnt lgkmcnt(8)
	v_mfma_f32_16x16x32_bf16 v[82:85], v[114:117], v[74:77], v[118:121]
	global_store_dwordx2 v[170:171], v[58:59], off offset:32
	s_nop 1
	v_cvt_pk_bf16_f32 v58, v106, v107
	v_cvt_pk_bf16_f32 v59, v108, v109
	s_waitcnt lgkmcnt(5)
	v_mfma_f32_16x16x32_bf16 v[142:145], v[134:137], v[60:63], 0
	global_store_dwordx2 v[170:171], v[58:59], off offset:64
	v_cvt_pk_bf16_f32 v58, v82, v83
	v_cvt_pk_bf16_f32 v59, v84, v85
	v_mfma_f32_16x16x32_bf16 v[130:133], v[122:125], v[60:63], 0
	ds_read_b128 v[82:85], v54 offset:38144
	global_store_dwordx2 v[170:171], v[58:59], off offset:96
	v_and_b32_e32 v52, 0xfc, v52
	s_waitcnt lgkmcnt(4)
	v_mfma_f32_16x16x32_bf16 v[154:157], v[146:149], v[60:63], 0
	v_lshl_add_u64 v[26:27], v[26:27], 1, s[10:11]
	s_and_b64 vcc, exec, s[12:13]
	s_mov_b32 s14, s39
	s_waitcnt lgkmcnt(2)
	v_mfma_f32_16x16x32_bf16 v[60:63], v[158:161], v[60:63], 0
	v_mfma_f32_16x16x32_bf16 v[94:97], v[138:141], v[74:77], v[142:145]
	v_mfma_f32_16x16x32_bf16 v[118:121], v[126:129], v[74:77], v[130:133]
	v_mfma_f32_16x16x32_bf16 v[106:109], v[150:153], v[74:77], v[154:157]
	s_nop 5
	v_cvt_pk_bf16_f32 v55, v96, v97
	s_waitcnt lgkmcnt(1)
	v_mfma_f32_16x16x32_bf16 v[58:61], v[162:165], v[74:77], v[60:63]
	ds_read_b128 v[74:77], v54 offset:38208
	v_cvt_pk_bf16_f32 v54, v94, v95
	global_store_dwordx2 v[170:171], v[54:55], off offset:160
	s_waitcnt lgkmcnt(1)
	v_mfma_f32_16x16x32_bf16 v[68:71], v[70:73], v[82:85], 0
	v_cvt_pk_bf16_f32 v54, v106, v107
	v_cvt_pk_bf16_f32 v55, v108, v109
	global_store_dwordx2 v[170:171], v[54:55], off offset:192
	v_cvt_pk_bf16_f32 v54, v58, v59
	v_cvt_pk_bf16_f32 v55, v60, v61
	s_waitcnt lgkmcnt(0)
	v_mfma_f32_16x16x32_bf16 v[58:61], v[78:81], v[74:77], v[68:71]
	global_store_dwordx2 v[170:171], v[54:55], off offset:224
	v_lshl_add_u64 v[54:55], v[166:167], 0, s[4:5]
	v_cvt_pk_bf16_f32 v62, v118, v119
	v_mfma_f32_16x16x32_bf16 v[86:89], v[86:89], v[82:85], 0
	v_cvt_pk_bf16_f32 v63, v120, v121
	s_nop 2
	v_cvt_pk_bf16_f32 v58, v58, v59
	v_cvt_pk_bf16_f32 v59, v60, v61
	v_lshl_add_u64 v[60:61], v[54:55], 0, v[168:169]
	v_mfma_f32_16x16x32_bf16 v[94:97], v[98:101], v[82:85], 0
	global_store_dwordx2 v[60:61], v[58:59], off
	global_store_dwordx2 v[170:171], v[62:63], off offset:128
	v_or_b32_e32 v72, 32, v168
	v_mfma_f32_16x16x32_bf16 v[58:61], v[90:93], v[74:77], v[86:89]
	v_mov_b32_e32 v73, v24
	v_lshl_add_u64 v[72:73], v[54:55], 0, v[72:73]
	v_mfma_f32_16x16x32_bf16 v[68:71], v[110:113], v[82:85], 0
	v_mfma_f32_16x16x32_bf16 v[78:81], v[102:105], v[74:77], v[94:97]
	s_nop 3
	v_cvt_pk_bf16_f32 v62, v58, v59
	v_cvt_pk_bf16_f32 v63, v60, v61
	global_store_dwordx2 v[72:73], v[62:63], off
	v_mfma_f32_16x16x32_bf16 v[58:61], v[122:125], v[82:85], 0
	v_or_b32_e32 v72, 64, v168
	v_mov_b32_e32 v73, v24
	v_cvt_pk_bf16_f32 v62, v78, v79
	v_mfma_f32_16x16x32_bf16 v[68:71], v[114:117], v[74:77], v[68:71]
	v_cvt_pk_bf16_f32 v63, v80, v81
	v_lshl_add_u64 v[72:73], v[54:55], 0, v[72:73]
	global_store_dwordx2 v[72:73], v[62:63], off
	v_mfma_f32_16x16x32_bf16 v[58:61], v[126:129], v[74:77], v[58:61]
	v_or_b32_e32 v72, 0x60, v168
	v_mov_b32_e32 v73, v24
	s_nop 1
	v_cvt_pk_bf16_f32 v62, v68, v69
	v_cvt_pk_bf16_f32 v63, v70, v71
	v_lshl_add_u64 v[72:73], v[54:55], 0, v[72:73]
	global_store_dwordx2 v[72:73], v[62:63], off
	v_or_b32_e32 v72, 0x80, v168
	v_mov_b32_e32 v73, v24
	v_cvt_pk_bf16_f32 v62, v58, v59
	v_cvt_pk_bf16_f32 v63, v60, v61
	v_lshl_add_u64 v[72:73], v[54:55], 0, v[72:73]
	v_mfma_f32_16x16x32_bf16 v[78:81], v[134:137], v[82:85], 0
	global_store_dwordx2 v[72:73], v[62:63], off
	v_mul_lo_u32 v62, v65, s35
	v_or_b32_e32 v102, 0xa0, v168
	v_mfma_f32_16x16x32_bf16 v[68:71], v[146:149], v[82:85], 0
	v_mov_b32_e32 v103, v24
	v_lshl_add_u64 v[112:113], v[54:55], 0, v[102:103]
	v_or_b32_e32 v136, 0xc0, v168
	v_mfma_f32_16x16x32_bf16 v[58:61], v[158:161], v[82:85], 0
	v_lshl_add_u32 v82, v66, 1, v62
	ds_read_b128 v[62:65], v82 offset:54272
	v_mov_b32_e32 v137, v24
	v_mfma_f32_16x16x32_bf16 v[78:81], v[138:141], v[74:77], v[78:81]
	v_mfma_f32_16x16x32_bf16 v[66:69], v[150:153], v[74:77], v[68:71]
	s_nop 2
	ds_read_b128 v[70:73], v56 offset:35840
	s_nop 2
	v_cvt_pk_bf16_f32 v110, v78, v79
	v_cvt_pk_bf16_f32 v111, v80, v81
	v_mfma_f32_16x16x32_bf16 v[58:61], v[162:165], v[74:77], v[58:61]
	ds_read_b128 v[74:77], v56 offset:38144
	ds_read_b128 v[78:81], v82 offset:54336
	ds_read_b128 v[82:85], v56 offset:35904
	ds_read_b128 v[86:89], v56 offset:40448
	ds_read_b128 v[90:93], v56 offset:38208
	ds_read_b128 v[94:97], v56 offset:42752
	ds_read_b128 v[98:101], v56 offset:40512
	ds_read_b128 v[102:105], v56 offset:45056
	ds_read_b128 v[106:109], v56 offset:42816
	global_store_dwordx2 v[112:113], v[110:111], off
	ds_read_b128 v[110:113], v56 offset:47360
	ds_read_b128 v[114:117], v56 offset:45120
	v_cvt_pk_bf16_f32 v134, v66, v67
	ds_read_b128 v[118:121], v56 offset:49664
	ds_read_b128 v[122:125], v56 offset:47424
	v_cvt_pk_bf16_f32 v135, v68, v69
	ds_read_b128 v[66:69], v56 offset:51968
	ds_read_b128 v[126:129], v56 offset:49728
	s_waitcnt lgkmcnt(14)
	v_mfma_f32_16x16x32_bf16 v[70:73], v[70:73], v[62:65], 0
	ds_read_b128 v[130:133], v56 offset:52032
	v_mfma_f32_16x16x32_bf16 v[74:77], v[74:77], v[62:65], 0
	s_waitcnt lgkmcnt(12)
	v_mfma_f32_16x16x32_bf16 v[86:89], v[86:89], v[62:65], 0
	s_waitcnt lgkmcnt(10)
	v_mfma_f32_16x16x32_bf16 v[94:97], v[94:97], v[62:65], 0
	s_waitcnt lgkmcnt(8)
	v_mfma_f32_16x16x32_bf16 v[102:105], v[102:105], v[62:65], 0
	s_waitcnt lgkmcnt(6)
	v_mfma_f32_16x16x32_bf16 v[110:113], v[110:113], v[62:65], 0
	s_waitcnt lgkmcnt(4)
	v_mfma_f32_16x16x32_bf16 v[118:121], v[118:121], v[62:65], 0
	s_waitcnt lgkmcnt(2)
	v_mfma_f32_16x16x32_bf16 v[62:65], v[66:69], v[62:65], 0
	v_lshl_add_u64 v[66:67], v[54:55], 0, v[136:137]
	global_store_dwordx2 v[66:67], v[134:135], off
	v_cvt_pk_bf16_f32 v134, v58, v59
	v_mfma_f32_16x16x32_bf16 v[66:69], v[82:85], v[78:81], v[70:73]
	v_cvt_pk_bf16_f32 v135, v60, v61
	v_mfma_f32_16x16x32_bf16 v[58:61], v[90:93], v[78:81], v[74:77]
	s_nop 0
	v_or_b32_e32 v70, 0xe0, v168
	v_mov_b32_e32 v71, v24
	v_lshl_add_u64 v[54:55], v[54:55], 0, v[70:71]
	v_lshl_or_b32 v76, v53, 11, v52
	v_ashrrev_i32_e32 v77, 31, v76
	global_store_dwordx2 v[54:55], v[134:135], off
	v_cvt_pk_bf16_f32 v74, v66, v67
	v_cvt_pk_bf16_f32 v75, v68, v69
	v_mfma_f32_16x16x32_bf16 v[52:55], v[114:117], v[78:81], v[102:105]
	v_lshl_add_u64 v[26:27], v[76:77], 1, v[26:27]
	global_store_dwordx2 v[26:27], v[74:75], off
	v_cvt_pk_bf16_f32 v58, v58, v59
	v_mfma_f32_16x16x32_bf16 v[74:77], v[122:125], v[78:81], v[110:113]
	v_cvt_pk_bf16_f32 v59, v60, v61
	global_store_dwordx2 v[26:27], v[58:59], off offset:512
	s_nop 1
	v_cvt_pk_bf16_f32 v52, v52, v53
	s_waitcnt lgkmcnt(1)
	v_mfma_f32_16x16x32_bf16 v[58:61], v[126:129], v[78:81], v[118:121]
	v_cvt_pk_bf16_f32 v53, v54, v55
	global_store_dwordx2 v[26:27], v[52:53], off offset:2048
	v_cvt_pk_bf16_f32 v52, v74, v75
	s_waitcnt lgkmcnt(0)
	v_mfma_f32_16x16x32_bf16 v[62:65], v[130:133], v[78:81], v[62:65]
	v_cvt_pk_bf16_f32 v53, v76, v77
	global_store_dwordx2 v[26:27], v[52:53], off offset:2560
	s_nop 0
	v_cvt_pk_bf16_f32 v52, v58, v59
	v_mfma_f32_16x16x32_bf16 v[70:73], v[98:101], v[78:81], v[86:89]
	v_cvt_pk_bf16_f32 v53, v60, v61
	global_store_dwordx2 v[26:27], v[52:53], off offset:3072
	s_nop 0
	v_cvt_pk_bf16_f32 v52, v62, v63
	v_mfma_f32_16x16x32_bf16 v[66:69], v[106:109], v[78:81], v[94:97]
	v_cvt_pk_bf16_f32 v53, v64, v65
	s_nop 1
	v_cvt_pk_bf16_f32 v70, v70, v71
	v_cvt_pk_bf16_f32 v71, v72, v73
	global_store_dwordx2 v[26:27], v[52:53], off offset:3584
	s_waitcnt vmcnt(26)
	v_mov_b32_e32 v53, v25
	v_cvt_pk_bf16_f32 v66, v66, v67
	v_cvt_pk_bf16_f32 v67, v68, v69
	v_mov_b32_e32 v60, v57
	global_store_dwordx2 v[26:27], v[70:71], off offset:1024
	global_store_dwordx2 v[26:27], v[66:67], off offset:1536
	s_cbranch_vccnz .LBB0_904

.LBB0_1085:
	s_or_b64 exec, exec, s[0:1]
	s_cmpk_gt_i32 s2, 0x8bf
	s_barrier
	s_cbranch_scc1 .LBB0_1096
	s_add_u32 s13, s20, 0x17348000
	s_addc_u32 s15, s21, 0
	s_add_u32 s29, s20, 0x15248000
	s_addc_u32 s39, s21, 0
	s_add_u32 s46, s50, 0x4200000
	s_addc_u32 s47, s51, 0
	s_add_u32 s56, s50, 0x2100000
	s_addc_u32 s57, s51, 0
	s_waitcnt vmcnt(27)
	v_mbcnt_hi_u32_b32 v40, -1, v183
	s_add_u32 s58, s20, 0x19448000
	v_and_b32_e32 v0, 64, v40
	s_addc_u32 s59, s21, 0
	s_lshl_b32 s60, s2, 7
	s_lshl_b32 s61, s22, 7
	s_movk_i32 s62, 0x6000
	s_mov_b32 s7, 0
	v_mov_b32_e32 v33, 0
	s_mov_b64 s[8:9], 0x1000
	s_mov_b64 s[10:11], 0x1800
	s_movk_i32 s63, 0x1000
	s_mov_b32 s12, 0x3c800000
	s_mov_b32 s14, 0x358637bd
	s_mov_b32 s64, 0x800000
	s_movk_i32 s65, 0x2000
	s_movk_i32 s66, 0x4000
	s_mov_b64 s[16:17], 0x1c00
	s_movk_i32 s67, 0x3000
	s_movk_i32 s68, 0x5000
	s_movk_i32 s69, 0x7000
	s_mov_b64 s[34:35], 0x80
	s_mov_b64 s[36:37], 0xc0
	s_brev_b32 s38, 60
	v_xor_b32_e32 v41, 1, v40
	v_add_u32_e32 v42, 64, v0
	v_xor_b32_e32 v43, 2, v40
	s_waitcnt vmcnt(26)
	v_xor_b32_e32 v44, 4, v40
	v_xor_b32_e32 v45, 8, v40
	s_mov_b32 s70, s2
	v_bfe_u32 v232, v181, 4, 2
	v_lshlrev_b32_e32 v232, 4, v232
	global_load_dwordx4 v[184:187], v232, s[44:45]
	global_load_dwordx4 v[188:191], v232, s[44:45] offset:64
	global_load_dwordx4 v[192:195], v232, s[44:45] offset:128
	global_load_dwordx4 v[196:199], v232, s[44:45] offset:192
	global_load_dwordx4 v[200:203], v232, s[44:45] offset:256
	global_load_dwordx4 v[204:207], v232, s[44:45] offset:320
	global_load_dwordx4 v[208:211], v232, s[44:45] offset:384
	global_load_dwordx4 v[212:215], v232, s[44:45] offset:448
	s_branch .LBB0_1089

.LBB0_1094:
	s_ashr_i32 s4, s70, 2
	v_and_b32_e32 v0, 63, v181
	s_cmpk_gt_i32 s4, 0x1ff
	s_cselect_b64 s[0:1], -1, 0
	v_ashrrev_i32_e32 v1, 6, v181
	s_cmpk_lt_i32 s4, 0x200
	s_cselect_b64 s[24:25], -1, 0
	v_cmp_gt_i32_e32 vcc, 1, v1
	s_nop 1
	s_or_b64 s[42:43], s[24:25], vcc
	s_lshl_b32 s5, s4, 4
	s_addk_i32 s5, 0x6000
	s_lshl_b32 s6, s4, 6
	s_and_b64 s[0:1], s[0:1], exec
	s_cselect_b32 s0, s5, s6
	s_and_b32 s5, s70, 0xfffffe00
	s_bfe_u32 s6, s70, 0x70002
	s_and_b32 s1, s60, 0x180
	s_or_b32 s5, s6, s5
	s_or_b32 s5, s5, s1
	s_cmpk_lt_i32 s4, 0x200
	s_cselect_b32 s4, s5, s70
	s_ashr_i32 s5, s4, 31
	s_lshl_b64 s[24:25], s[4:5], 14
	s_add_u32 s30, s46, s24
	s_addc_u32 s31, s47, s25
	s_add_u32 s24, s56, s24
	s_addc_u32 s25, s57, s25
	s_lshl_b64 s[4:5], s[4:5], 15
	s_add_u32 s4, s58, s4
	s_addc_u32 s5, s59, s5
	v_and_b32_e32 v2, 15, v181
	v_bfe_u32 v3, v181, 4, 2
	v_lshlrev_b32_e32 v4, 3, v0
	v_lshl_add_u32 v4, v1, 12, v4
	v_lshl_add_u32 v5, v1, 4, v2
	v_lshlrev_b32_e32 v5, 8, v5
	v_lshl_add_u32 v5, v3, 4, v5
	v_lshlrev_b32_e32 v6, 4, v181
	v_add_u32_e32 v7, 0x1000, v6
	v_add_u32_e32 v8, 0x2000, v6
	v_add_u32_e32 v9, 0x3000, v6
	v_add_u32_e32 v10, 0x4000, v6
	v_add_u32_e32 v11, 0x5000, v6
	v_add_u32_e32 v12, 0x6000, v6
	v_add_u32_e32 v13, 0x7000, v6
	v_lshrrev_b32_e32 v16, 4, v181
	v_mul_u32_u24_e32 v16, 272, v16
	v_lshl_add_u32 v16, v2, 4, v16
	v_mul_u32_u24_e32 v233, 272, v2
	v_lshl_add_u32 v233, v3, 4, v233
	v_lshl_add_u32 v14, v1, 4, s0
	v_add_u32_e32 v14, v14, v2
	v_lshlrev_b32_e32 v14, 13, v14
	v_lshlrev_b32_e32 v15, 3, v3
	v_add_u32_e32 v14, v14, v15
	s_lshl_b32 s6, s1, 1
	s_add_i32 s6, s6, 0x400
	v_add_u32_e32 v232, s6, v14
	v_add_u32_e32 v14, 0x1800, v232
	global_load_dwordx2 v[62:63], v4, s[30:31]
	global_load_dwordx2 v[64:65], v4, s[30:31] offset:512
	global_load_dwordx2 v[66:67], v4, s[30:31] offset:1024
	global_load_dwordx2 v[68:69], v4, s[30:31] offset:1536
	global_load_dwordx2 v[70:71], v4, s[30:31] offset:2048
	global_load_dwordx2 v[72:73], v4, s[30:31] offset:2560
	global_load_dwordx2 v[74:75], v4, s[30:31] offset:3072
	global_load_dwordx2 v[76:77], v4, s[30:31] offset:3584
	global_load_dwordx4 v[46:49], v5, s[24:25]
	global_load_dwordx4 v[50:53], v5, s[24:25] offset:64
	global_load_dwordx4 v[54:57], v5, s[24:25] offset:128
	global_load_dwordx4 v[58:61], v5, s[24:25] offset:192
	global_load_dwordx2 v[216:217], v14, s[20:21]
	global_load_dwordx2 v[218:219], v14, s[20:21] offset:32
	global_load_dwordx2 v[220:221], v14, s[20:21] offset:64
	global_load_dwordx2 v[222:223], v14, s[20:21] offset:96
	global_load_dwordx2 v[224:225], v14, s[20:21] offset:128
	global_load_dwordx2 v[226:227], v14, s[20:21] offset:160
	global_load_dwordx2 v[228:229], v14, s[20:21] offset:192
	global_load_dwordx2 v[230:231], v14, s[20:21] offset:224
	global_load_dwordx4 v[78:81], v6, s[4:5]
	global_load_dwordx4 v[82:85], v7, s[4:5]
	global_load_dwordx4 v[86:89], v8, s[4:5]
	global_load_dwordx4 v[90:93], v9, s[4:5]
	global_load_dwordx4 v[94:97], v10, s[4:5]
	global_load_dwordx4 v[98:101], v11, s[4:5]
	global_load_dwordx4 v[102:105], v12, s[4:5]
	global_load_dwordx4 v[106:109], v13, s[4:5]
	s_barrier
	s_waitcnt vmcnt(0)
	ds_write_b128 v16, v[78:81]
	ds_write_b128 v16, v[82:85] offset:4352
	ds_write_b128 v16, v[86:89] offset:8704
	ds_write_b128 v16, v[90:93] offset:13056
	ds_write_b128 v16, v[94:97] offset:17408
	ds_write_b128 v16, v[98:101] offset:21760
	ds_write_b128 v16, v[102:105] offset:26112
	ds_write_b128 v16, v[106:109] offset:30464
	s_waitcnt lgkmcnt(0)
	s_barrier
	s_mov_b64 vcc, s[42:43]
	s_and_saveexec_b64 s[42:43], vcc
	s_cbranch_execz .LBB0_1087
	v_lshlrev_b32_e32 v28, 16, v62
	v_and_b32_e32 v29, 0xffff0000, v62
	v_lshlrev_b32_e32 v30, 16, v63
	v_and_b32_e32 v31, 0xffff0000, v63
	v_lshlrev_b32_e32 v24, 16, v64
	v_and_b32_e32 v25, 0xffff0000, v64
	v_lshlrev_b32_e32 v26, 16, v65
	v_and_b32_e32 v27, 0xffff0000, v65
	v_lshlrev_b32_e32 v20, 16, v66
	v_and_b32_e32 v21, 0xffff0000, v66
	v_lshlrev_b32_e32 v22, 16, v67
	v_and_b32_e32 v23, 0xffff0000, v67
	v_lshlrev_b32_e32 v16, 16, v68
	v_and_b32_e32 v17, 0xffff0000, v68
	v_lshlrev_b32_e32 v18, 16, v69
	v_and_b32_e32 v19, 0xffff0000, v69
	v_lshlrev_b32_e32 v12, 16, v70
	v_and_b32_e32 v13, 0xffff0000, v70
	v_lshlrev_b32_e32 v14, 16, v71
	v_and_b32_e32 v15, 0xffff0000, v71
	v_lshlrev_b32_e32 v8, 16, v72
	v_and_b32_e32 v9, 0xffff0000, v72
	v_lshlrev_b32_e32 v10, 16, v73
	v_and_b32_e32 v11, 0xffff0000, v73
	v_lshlrev_b32_e32 v4, 16, v74
	v_and_b32_e32 v5, 0xffff0000, v74
	v_lshlrev_b32_e32 v6, 16, v75
	v_and_b32_e32 v7, 0xffff0000, v75
	v_lshlrev_b32_e32 v0, 16, v76
	v_and_b32_e32 v1, 0xffff0000, v76
	v_lshlrev_b32_e32 v2, 16, v77
	v_and_b32_e32 v3, 0xffff0000, v77
	ds_read_b128 v[78:81], v233 offset:0
	ds_read_b128 v[82:85], v233 offset:4352
	ds_read_b128 v[86:89], v233 offset:8704
	ds_read_b128 v[90:93], v233 offset:13056
	ds_read_b128 v[94:97], v233 offset:17408
	ds_read_b128 v[98:101], v233 offset:21760
	ds_read_b128 v[102:105], v233 offset:26112
	ds_read_b128 v[106:109], v233 offset:30464
	s_waitcnt lgkmcnt(4)
	ds_read_b128 v[110:113], v233 offset:64
	ds_read_b128 v[114:117], v233 offset:4416
	ds_read_b128 v[118:121], v233 offset:8768
	ds_read_b128 v[122:125], v233 offset:13120
	ds_read_b128 v[126:129], v233 offset:17472
	ds_read_b128 v[130:133], v233 offset:21824
	ds_read_b128 v[134:137], v233 offset:26176
	ds_read_b128 v[138:141], v233 offset:30528
	s_waitcnt lgkmcnt(8)
	v_mfma_f32_16x16x32_bf16 v[28:31], v[78:81], v[46:49], v[28:31]
	v_mfma_f32_16x16x32_bf16 v[24:27], v[82:85], v[46:49], v[24:27]
	v_mfma_f32_16x16x32_bf16 v[20:23], v[86:89], v[46:49], v[20:23]
	v_mfma_f32_16x16x32_bf16 v[16:19], v[90:93], v[46:49], v[16:19]
	v_mfma_f32_16x16x32_bf16 v[12:15], v[94:97], v[46:49], v[12:15]
	v_mfma_f32_16x16x32_bf16 v[8:11], v[98:101], v[46:49], v[8:11]
	v_mfma_f32_16x16x32_bf16 v[4:7], v[102:105], v[46:49], v[4:7]
	v_mfma_f32_16x16x32_bf16 v[0:3], v[106:109], v[46:49], v[0:3]
	s_waitcnt lgkmcnt(4)
	ds_read_b128 v[78:81], v233 offset:128
	ds_read_b128 v[82:85], v233 offset:4480
	ds_read_b128 v[86:89], v233 offset:8832
	ds_read_b128 v[90:93], v233 offset:13184
	ds_read_b128 v[94:97], v233 offset:17536
	ds_read_b128 v[98:101], v233 offset:21888
	ds_read_b128 v[102:105], v233 offset:26240
	ds_read_b128 v[106:109], v233 offset:30592
	s_waitcnt lgkmcnt(8)
	v_mfma_f32_16x16x32_bf16 v[28:31], v[110:113], v[50:53], v[28:31]
	v_mfma_f32_16x16x32_bf16 v[24:27], v[114:117], v[50:53], v[24:27]
	v_mfma_f32_16x16x32_bf16 v[20:23], v[118:121], v[50:53], v[20:23]
	v_mfma_f32_16x16x32_bf16 v[16:19], v[122:125], v[50:53], v[16:19]
	v_mfma_f32_16x16x32_bf16 v[12:15], v[126:129], v[50:53], v[12:15]
	v_mfma_f32_16x16x32_bf16 v[8:11], v[130:133], v[50:53], v[8:11]
	v_mfma_f32_16x16x32_bf16 v[4:7], v[134:137], v[50:53], v[4:7]
	v_mfma_f32_16x16x32_bf16 v[0:3], v[138:141], v[50:53], v[0:3]
	s_waitcnt lgkmcnt(4)
	ds_read_b128 v[110:113], v233 offset:192
	ds_read_b128 v[114:117], v233 offset:4544
	ds_read_b128 v[118:121], v233 offset:8896
	ds_read_b128 v[122:125], v233 offset:13248
	ds_read_b128 v[126:129], v233 offset:17600
	ds_read_b128 v[130:133], v233 offset:21952
	ds_read_b128 v[134:137], v233 offset:26304
	ds_read_b128 v[138:141], v233 offset:30656
	s_waitcnt lgkmcnt(8)
	v_mfma_f32_16x16x32_bf16 v[28:31], v[78:81], v[54:57], v[28:31]
	v_mfma_f32_16x16x32_bf16 v[24:27], v[82:85], v[54:57], v[24:27]
	v_mfma_f32_16x16x32_bf16 v[20:23], v[86:89], v[54:57], v[20:23]
	v_mfma_f32_16x16x32_bf16 v[16:19], v[90:93], v[54:57], v[16:19]
	v_mfma_f32_16x16x32_bf16 v[12:15], v[94:97], v[54:57], v[12:15]
	v_mfma_f32_16x16x32_bf16 v[8:11], v[98:101], v[54:57], v[8:11]
	v_mfma_f32_16x16x32_bf16 v[4:7], v[102:105], v[54:57], v[4:7]
	v_mfma_f32_16x16x32_bf16 v[0:3], v[106:109], v[54:57], v[0:3]
	s_waitcnt lgkmcnt(0)
	v_mfma_f32_16x16x32_bf16 v[28:31], v[110:113], v[58:61], v[28:31]
	v_mfma_f32_16x16x32_bf16 v[24:27], v[114:117], v[58:61], v[24:27]
	v_mfma_f32_16x16x32_bf16 v[20:23], v[118:121], v[58:61], v[20:23]
	v_mfma_f32_16x16x32_bf16 v[16:19], v[122:125], v[58:61], v[16:19]
	v_mfma_f32_16x16x32_bf16 v[12:15], v[126:129], v[58:61], v[12:15]
	v_mfma_f32_16x16x32_bf16 v[8:11], v[130:133], v[58:61], v[8:11]
	v_mfma_f32_16x16x32_bf16 v[4:7], v[134:137], v[58:61], v[4:7]
	v_mfma_f32_16x16x32_bf16 v[0:3], v[138:141], v[58:61], v[0:3]
	v_xor_b32_e32 v241, 16, v40
	v_xor_b32_e32 v242, 32, v40
	v_lshlrev_b32_e32 v241, 2, v241
	v_lshlrev_b32_e32 v242, 2, v242
	s_nop 4
	v_mul_f32_e32 v46, v28, v28
	v_fmac_f32_e32 v46, v29, v29
	v_fmac_f32_e32 v46, v30, v30
	v_fmac_f32_e32 v46, v31, v31
	v_fmac_f32_e32 v46, v24, v24
	v_fmac_f32_e32 v46, v25, v25
	v_fmac_f32_e32 v46, v26, v26
	v_fmac_f32_e32 v46, v27, v27
	v_fmac_f32_e32 v46, v20, v20
	v_fmac_f32_e32 v46, v21, v21
	v_fmac_f32_e32 v46, v22, v22
	v_fmac_f32_e32 v46, v23, v23
	v_fmac_f32_e32 v46, v16, v16
	v_fmac_f32_e32 v46, v17, v17
	v_fmac_f32_e32 v46, v18, v18
	v_fmac_f32_e32 v46, v19, v19
	v_fmac_f32_e32 v46, v12, v12
	v_fmac_f32_e32 v46, v13, v13
	v_fmac_f32_e32 v46, v14, v14
	v_fmac_f32_e32 v46, v15, v15
	v_fmac_f32_e32 v46, v8, v8
	v_fmac_f32_e32 v46, v9, v9
	v_fmac_f32_e32 v46, v10, v10
	v_fmac_f32_e32 v46, v11, v11
	v_fmac_f32_e32 v46, v4, v4
	v_fmac_f32_e32 v46, v5, v5
	v_fmac_f32_e32 v46, v6, v6
	v_fmac_f32_e32 v46, v7, v7
	v_fmac_f32_e32 v46, v0, v0
	v_fmac_f32_e32 v46, v1, v1
	v_fmac_f32_e32 v46, v2, v2
	v_fmac_f32_e32 v46, v3, v3
	ds_bpermute_b32 v47, v241, v46
	s_waitcnt lgkmcnt(0)
	v_add_f32_e32 v46, v46, v47
	ds_bpermute_b32 v47, v242, v46
	s_waitcnt lgkmcnt(0)
	v_add_f32_e32 v46, v46, v47
	v_mov_b32_e32 v50, 0x358637bd
	v_fmamk_f32 v46, v46, 0x3c000000, v50
	v_rsq_f32_e32 v46, v46
	v_lshlrev_b32_e32 v48, 16, v216
	v_and_b32_e32 v49, 0xffff0000, v216
	v_lshlrev_b32_e32 v50, 16, v217
	v_and_b32_e32 v51, 0xffff0000, v217
	v_mul_f32_e32 v52, 0xbfb8aa3b, v48
	v_mul_f32_e32 v53, 0xbfb8aa3b, v49
	v_mul_f32_e32 v54, 0xbfb8aa3b, v50
	v_mul_f32_e32 v55, 0xbfb8aa3b, v51
	v_exp_f32_e32 v52, v52
	v_exp_f32_e32 v53, v53
	v_exp_f32_e32 v54, v54
	v_exp_f32_e32 v55, v55
	v_mul_f32_e32 v56, v28, v46
	v_mul_f32_e32 v57, v29, v46
	v_mul_f32_e32 v58, v30, v46
	v_mul_f32_e32 v59, v31, v46
	v_add_f32_e32 v52, 1.0, v52
	v_add_f32_e32 v53, 1.0, v53
	v_add_f32_e32 v54, 1.0, v54
	v_add_f32_e32 v55, 1.0, v55
	v_rcp_f32_e32 v52, v52
	v_rcp_f32_e32 v53, v53
	v_rcp_f32_e32 v54, v54
	v_rcp_f32_e32 v55, v55
	v_mul_f32_e32 v56, v184, v56
	v_mul_f32_e32 v57, v185, v57
	v_mul_f32_e32 v58, v186, v58
	v_mul_f32_e32 v59, v187, v59
	v_mul_f32_e32 v52, v52, v48
	v_mul_f32_e32 v53, v53, v49
	v_mul_f32_e32 v54, v54, v50
	v_mul_f32_e32 v55, v55, v51
	v_mul_f32_e32 v56, v52, v56
	v_mul_f32_e32 v57, v53, v57
	v_mul_f32_e32 v58, v54, v58
	v_mul_f32_e32 v59, v55, v59
	v_cvt_pk_bf16_f32 v60, v56, v57
	v_cvt_pk_bf16_f32 v61, v58, v59
	global_store_dwordx2 v232, v[60:61], s[20:21]
	v_lshlrev_b32_e32 v48, 16, v218
	v_and_b32_e32 v49, 0xffff0000, v218
	v_lshlrev_b32_e32 v50, 16, v219
	v_and_b32_e32 v51, 0xffff0000, v219
	v_mul_f32_e32 v52, 0xbfb8aa3b, v48
	v_mul_f32_e32 v53, 0xbfb8aa3b, v49
	v_mul_f32_e32 v54, 0xbfb8aa3b, v50
	v_mul_f32_e32 v55, 0xbfb8aa3b, v51
	v_exp_f32_e32 v52, v52
	v_exp_f32_e32 v53, v53
	v_exp_f32_e32 v54, v54
	v_exp_f32_e32 v55, v55
	v_mul_f32_e32 v56, v24, v46
	v_mul_f32_e32 v57, v25, v46
	v_mul_f32_e32 v58, v26, v46
	v_mul_f32_e32 v59, v27, v46
	v_add_f32_e32 v52, 1.0, v52
	v_add_f32_e32 v53, 1.0, v53
	v_add_f32_e32 v54, 1.0, v54
	v_add_f32_e32 v55, 1.0, v55
	v_rcp_f32_e32 v52, v52
	v_rcp_f32_e32 v53, v53
	v_rcp_f32_e32 v54, v54
	v_rcp_f32_e32 v55, v55
	v_mul_f32_e32 v56, v188, v56
	v_mul_f32_e32 v57, v189, v57
	v_mul_f32_e32 v58, v190, v58
	v_mul_f32_e32 v59, v191, v59
	v_mul_f32_e32 v52, v52, v48
	v_mul_f32_e32 v53, v53, v49
	v_mul_f32_e32 v54, v54, v50
	v_mul_f32_e32 v55, v55, v51
	v_mul_f32_e32 v56, v52, v56
	v_mul_f32_e32 v57, v53, v57
	v_mul_f32_e32 v58, v54, v58
	v_mul_f32_e32 v59, v55, v59
	v_cvt_pk_bf16_f32 v60, v56, v57
	v_cvt_pk_bf16_f32 v61, v58, v59
	global_store_dwordx2 v232, v[60:61], s[20:21] offset:32
	v_lshlrev_b32_e32 v48, 16, v220
	v_and_b32_e32 v49, 0xffff0000, v220
	v_lshlrev_b32_e32 v50, 16, v221
	v_and_b32_e32 v51, 0xffff0000, v221
	v_mul_f32_e32 v52, 0xbfb8aa3b, v48
	v_mul_f32_e32 v53, 0xbfb8aa3b, v49
	v_mul_f32_e32 v54, 0xbfb8aa3b, v50
	v_mul_f32_e32 v55, 0xbfb8aa3b, v51
	v_exp_f32_e32 v52, v52
	v_exp_f32_e32 v53, v53
	v_exp_f32_e32 v54, v54
	v_exp_f32_e32 v55, v55
	v_mul_f32_e32 v56, v20, v46
	v_mul_f32_e32 v57, v21, v46
	v_mul_f32_e32 v58, v22, v46
	v_mul_f32_e32 v59, v23, v46
	v_add_f32_e32 v52, 1.0, v52
	v_add_f32_e32 v53, 1.0, v53
	v_add_f32_e32 v54, 1.0, v54
	v_add_f32_e32 v55, 1.0, v55
	v_rcp_f32_e32 v52, v52
	v_rcp_f32_e32 v53, v53
	v_rcp_f32_e32 v54, v54
	v_rcp_f32_e32 v55, v55
	v_mul_f32_e32 v56, v192, v56
	v_mul_f32_e32 v57, v193, v57
	v_mul_f32_e32 v58, v194, v58
	v_mul_f32_e32 v59, v195, v59
	v_mul_f32_e32 v52, v52, v48
	v_mul_f32_e32 v53, v53, v49
	v_mul_f32_e32 v54, v54, v50
	v_mul_f32_e32 v55, v55, v51
	v_mul_f32_e32 v56, v52, v56
	v_mul_f32_e32 v57, v53, v57
	v_mul_f32_e32 v58, v54, v58
	v_mul_f32_e32 v59, v55, v59
	v_cvt_pk_bf16_f32 v60, v56, v57
	v_cvt_pk_bf16_f32 v61, v58, v59
	global_store_dwordx2 v232, v[60:61], s[20:21] offset:64
	v_lshlrev_b32_e32 v48, 16, v222
	v_and_b32_e32 v49, 0xffff0000, v222
	v_lshlrev_b32_e32 v50, 16, v223
	v_and_b32_e32 v51, 0xffff0000, v223
	v_mul_f32_e32 v52, 0xbfb8aa3b, v48
	v_mul_f32_e32 v53, 0xbfb8aa3b, v49
	v_mul_f32_e32 v54, 0xbfb8aa3b, v50
	v_mul_f32_e32 v55, 0xbfb8aa3b, v51
	v_exp_f32_e32 v52, v52
	v_exp_f32_e32 v53, v53
	v_exp_f32_e32 v54, v54
	v_exp_f32_e32 v55, v55
	v_mul_f32_e32 v56, v16, v46
	v_mul_f32_e32 v57, v17, v46
	v_mul_f32_e32 v58, v18, v46
	v_mul_f32_e32 v59, v19, v46
	v_add_f32_e32 v52, 1.0, v52
	v_add_f32_e32 v53, 1.0, v53
	v_add_f32_e32 v54, 1.0, v54
	v_add_f32_e32 v55, 1.0, v55
	v_rcp_f32_e32 v52, v52
	v_rcp_f32_e32 v53, v53
	v_rcp_f32_e32 v54, v54
	v_rcp_f32_e32 v55, v55
	v_mul_f32_e32 v56, v196, v56
	v_mul_f32_e32 v57, v197, v57
	v_mul_f32_e32 v58, v198, v58
	v_mul_f32_e32 v59, v199, v59
	v_mul_f32_e32 v52, v52, v48
	v_mul_f32_e32 v53, v53, v49
	v_mul_f32_e32 v54, v54, v50
	v_mul_f32_e32 v55, v55, v51
	v_mul_f32_e32 v56, v52, v56
	v_mul_f32_e32 v57, v53, v57
	v_mul_f32_e32 v58, v54, v58
	v_mul_f32_e32 v59, v55, v59
	v_cvt_pk_bf16_f32 v60, v56, v57
	v_cvt_pk_bf16_f32 v61, v58, v59
	global_store_dwordx2 v232, v[60:61], s[20:21] offset:96
	v_lshlrev_b32_e32 v48, 16, v224
	v_and_b32_e32 v49, 0xffff0000, v224
	v_lshlrev_b32_e32 v50, 16, v225
	v_and_b32_e32 v51, 0xffff0000, v225
	v_mul_f32_e32 v52, 0xbfb8aa3b, v48
	v_mul_f32_e32 v53, 0xbfb8aa3b, v49
	v_mul_f32_e32 v54, 0xbfb8aa3b, v50
	v_mul_f32_e32 v55, 0xbfb8aa3b, v51
	v_exp_f32_e32 v52, v52
	v_exp_f32_e32 v53, v53
	v_exp_f32_e32 v54, v54
	v_exp_f32_e32 v55, v55
	v_mul_f32_e32 v56, v12, v46
	v_mul_f32_e32 v57, v13, v46
	v_mul_f32_e32 v58, v14, v46
	v_mul_f32_e32 v59, v15, v46
	v_add_f32_e32 v52, 1.0, v52
	v_add_f32_e32 v53, 1.0, v53
	v_add_f32_e32 v54, 1.0, v54
	v_add_f32_e32 v55, 1.0, v55
	v_rcp_f32_e32 v52, v52
	v_rcp_f32_e32 v53, v53
	v_rcp_f32_e32 v54, v54
	v_rcp_f32_e32 v55, v55
	v_mul_f32_e32 v56, v200, v56
	v_mul_f32_e32 v57, v201, v57
	v_mul_f32_e32 v58, v202, v58
	v_mul_f32_e32 v59, v203, v59
	v_mul_f32_e32 v52, v52, v48
	v_mul_f32_e32 v53, v53, v49
	v_mul_f32_e32 v54, v54, v50
	v_mul_f32_e32 v55, v55, v51
	v_mul_f32_e32 v56, v52, v56
	v_mul_f32_e32 v57, v53, v57
	v_mul_f32_e32 v58, v54, v58
	v_mul_f32_e32 v59, v55, v59
	v_cvt_pk_bf16_f32 v60, v56, v57
	v_cvt_pk_bf16_f32 v61, v58, v59
	global_store_dwordx2 v232, v[60:61], s[20:21] offset:128
	v_lshlrev_b32_e32 v48, 16, v226
	v_and_b32_e32 v49, 0xffff0000, v226
	v_lshlrev_b32_e32 v50, 16, v227
	v_and_b32_e32 v51, 0xffff0000, v227
	v_mul_f32_e32 v52, 0xbfb8aa3b, v48
	v_mul_f32_e32 v53, 0xbfb8aa3b, v49
	v_mul_f32_e32 v54, 0xbfb8aa3b, v50
	v_mul_f32_e32 v55, 0xbfb8aa3b, v51
	v_exp_f32_e32 v52, v52
	v_exp_f32_e32 v53, v53
	v_exp_f32_e32 v54, v54
	v_exp_f32_e32 v55, v55
	v_mul_f32_e32 v56, v8, v46
	v_mul_f32_e32 v57, v9, v46
	v_mul_f32_e32 v58, v10, v46
	v_mul_f32_e32 v59, v11, v46
	v_add_f32_e32 v52, 1.0, v52
	v_add_f32_e32 v53, 1.0, v53
	v_add_f32_e32 v54, 1.0, v54
	v_add_f32_e32 v55, 1.0, v55
	v_rcp_f32_e32 v52, v52
	v_rcp_f32_e32 v53, v53
	v_rcp_f32_e32 v54, v54
	v_rcp_f32_e32 v55, v55
	v_mul_f32_e32 v56, v204, v56
	v_mul_f32_e32 v57, v205, v57
	v_mul_f32_e32 v58, v206, v58
	v_mul_f32_e32 v59, v207, v59
	v_mul_f32_e32 v52, v52, v48
	v_mul_f32_e32 v53, v53, v49
	v_mul_f32_e32 v54, v54, v50
	v_mul_f32_e32 v55, v55, v51
	v_mul_f32_e32 v56, v52, v56
	v_mul_f32_e32 v57, v53, v57
	v_mul_f32_e32 v58, v54, v58
	v_mul_f32_e32 v59, v55, v59
	v_cvt_pk_bf16_f32 v60, v56, v57
	v_cvt_pk_bf16_f32 v61, v58, v59
	global_store_dwordx2 v232, v[60:61], s[20:21] offset:160
	v_lshlrev_b32_e32 v48, 16, v228
	v_and_b32_e32 v49, 0xffff0000, v228
	v_lshlrev_b32_e32 v50, 16, v229
	v_and_b32_e32 v51, 0xffff0000, v229
	v_mul_f32_e32 v52, 0xbfb8aa3b, v48
	v_mul_f32_e32 v53, 0xbfb8aa3b, v49
	v_mul_f32_e32 v54, 0xbfb8aa3b, v50
	v_mul_f32_e32 v55, 0xbfb8aa3b, v51
	v_exp_f32_e32 v52, v52
	v_exp_f32_e32 v53, v53
	v_exp_f32_e32 v54, v54
	v_exp_f32_e32 v55, v55
	v_mul_f32_e32 v56, v4, v46
	v_mul_f32_e32 v57, v5, v46
	v_mul_f32_e32 v58, v6, v46
	v_mul_f32_e32 v59, v7, v46
	v_add_f32_e32 v52, 1.0, v52
	v_add_f32_e32 v53, 1.0, v53
	v_add_f32_e32 v54, 1.0, v54
	v_add_f32_e32 v55, 1.0, v55
	v_rcp_f32_e32 v52, v52
	v_rcp_f32_e32 v53, v53
	v_rcp_f32_e32 v54, v54
	v_rcp_f32_e32 v55, v55
	v_mul_f32_e32 v56, v208, v56
	v_mul_f32_e32 v57, v209, v57
	v_mul_f32_e32 v58, v210, v58
	v_mul_f32_e32 v59, v211, v59
	v_mul_f32_e32 v52, v52, v48
	v_mul_f32_e32 v53, v53, v49
	v_mul_f32_e32 v54, v54, v50
	v_mul_f32_e32 v55, v55, v51
	v_mul_f32_e32 v56, v52, v56
	v_mul_f32_e32 v57, v53, v57
	v_mul_f32_e32 v58, v54, v58
	v_mul_f32_e32 v59, v55, v59
	v_cvt_pk_bf16_f32 v60, v56, v57
	v_cvt_pk_bf16_f32 v61, v58, v59
	global_store_dwordx2 v232, v[60:61], s[20:21] offset:192
	v_lshlrev_b32_e32 v48, 16, v230
	v_and_b32_e32 v49, 0xffff0000, v230
	v_lshlrev_b32_e32 v50, 16, v231
	v_and_b32_e32 v51, 0xffff0000, v231
	v_mul_f32_e32 v52, 0xbfb8aa3b, v48
	v_mul_f32_e32 v53, 0xbfb8aa3b, v49
	v_mul_f32_e32 v54, 0xbfb8aa3b, v50
	v_mul_f32_e32 v55, 0xbfb8aa3b, v51
	v_exp_f32_e32 v52, v52
	v_exp_f32_e32 v53, v53
	v_exp_f32_e32 v54, v54
	v_exp_f32_e32 v55, v55
	v_mul_f32_e32 v56, v0, v46
	v_mul_f32_e32 v57, v1, v46
	v_mul_f32_e32 v58, v2, v46
	v_mul_f32_e32 v59, v3, v46
	v_add_f32_e32 v52, 1.0, v52
	v_add_f32_e32 v53, 1.0, v53
	v_add_f32_e32 v54, 1.0, v54
	v_add_f32_e32 v55, 1.0, v55
	v_rcp_f32_e32 v52, v52
	v_rcp_f32_e32 v53, v53
	v_rcp_f32_e32 v54, v54
	v_rcp_f32_e32 v55, v55
	v_mul_f32_e32 v56, v212, v56
	v_mul_f32_e32 v57, v213, v57
	v_mul_f32_e32 v58, v214, v58
	v_mul_f32_e32 v59, v215, v59
	v_mul_f32_e32 v52, v52, v48
	v_mul_f32_e32 v53, v53, v49
	v_mul_f32_e32 v54, v54, v50
	v_mul_f32_e32 v55, v55, v51
	v_mul_f32_e32 v56, v52, v56
	v_mul_f32_e32 v57, v53, v57
	v_mul_f32_e32 v58, v54, v58
	v_mul_f32_e32 v59, v55, v59
	v_cvt_pk_bf16_f32 v60, v56, v57
	v_cvt_pk_bf16_f32 v61, v58, v59
	global_store_dwordx2 v232, v[60:61], s[20:21] offset:224
	s_branch .LBB0_1087
